# XCD-affine attention queue + scalar-base K/V staging + pipelined LDS fragment reads
# speedup vs baseline: 1.0106x; 1.0106x over previous
.LBB0_82:
	v_and_b32_e32 v230, 63, v157
	v_lshrrev_b32_e32 v231, 6, v157
	v_lshrrev_b32_e32 v232, 3, v230
	v_and_b32_e32 v233, 7, v230
	v_lshrrev_b32_e32 v230, 1, v232
	v_xor_b32_e32 v233, v233, v230
	v_lshlrev_b32_e32 v234, 4, v233
	v_xor_b32_e32 v233, 4, v233
	v_lshlrev_b32_e32 v235, 4, v233
	v_lshl_add_u32 v230, v231, 4, v232
	v_mul_u32_u24_e32 v226, 0x1d00, v230
	v_add_u32_e32 v226, v226, v234
	v_add_u32_e32 v230, 8, v230
	v_mul_u32_u24_e32 v227, 0x1d00, v230
	v_add_u32_e32 v227, v227, v235
	v_lshl_add_u32 v230, v231, 5, v232
	v_lshl_add_u32 v228, v230, 13, v234
	v_add_u32_e32 v230, 8, v230
	v_lshl_add_u32 v229, v230, 13, v235
	v_lshlrev_b32_e32 v230, 11, v231
	v_lshlrev_b32_e32 v231, 12, v231
	s_nop 0
	v_readfirstlane_b32 s76, v230
	v_readfirstlane_b32 s77, v231
	s_nop 0
	s_add_u32 s77, s77, 0x4000
	v_readlane_b32 s0, v253, 41
	v_readlane_b32 s2, v255, 16
	s_add_i32 s0, s2, s0
	s_and_b32 s2, s2, 3
	v_readlane_b32 s4, v253, 7
	s_lshl_b32 s1, s2, 10
	v_readlane_b32 s16, v253, 19
	v_and_b32_e32 v0, 63, v157
	v_readlane_b32 s17, v253, 20
	s_add_u32 s20, s16, s1
	s_addc_u32 s21, s17, 0
	v_lshlrev_b32_e32 v0, 2, v0
	global_load_dword v1, v0, s[20:21]
	global_load_dword v2, v0, s[20:21] offset:256
	v_readlane_b32 s3, v255, 17
	v_readlane_b32 s18, v253, 21
	v_readlane_b32 s19, v253, 22
	v_readlane_b32 s5, v253, 8
	v_readlane_b32 s6, v253, 9
	v_readlane_b32 s7, v253, 10
	v_readlane_b32 s8, v253, 11
	v_readlane_b32 s9, v253, 12
	v_readlane_b32 s10, v253, 13
	v_readlane_b32 s11, v253, 14
	v_readlane_b32 s12, v253, 15
	v_readlane_b32 s13, v253, 16
	v_readlane_b32 s14, v253, 17
	v_readlane_b32 s15, v253, 18
	s_waitcnt vmcnt(0)
	v_mul_f32_e32 v4, v1, v2
	s_nop 1
	v_mov_b32_dpp v4, v4 quad_perm:[1,0,3,2] row_mask:0xf bank_mask:0xf bound_ctrl:1
	v_fmac_f32_e32 v4, v1, v2
	v_mov_b32_e32 v2, v3
	s_nop 0
	v_add_f32_dpp v1, v4, v4 quad_perm:[2,3,0,1] row_mask:0xf bank_mask:0xf bound_ctrl:1
	s_nop 1
	v_add_f32_dpp v1, v1, v1 row_ror:4 row_mask:0xf bank_mask:0xf bound_ctrl:1
	s_nop 1
	v_add_f32_dpp v1, v1, v1 row_ror:8 row_mask:0xf bank_mask:0xf bound_ctrl:1
	s_nop 1
	v_mov_b32_dpp v2, v1 row_bcast:15 row_mask:0xa bank_mask:0xf bound_ctrl:1
	v_add_f32_e32 v1, v1, v2
	v_mov_b32_e32 v2, v3
	s_nop 1
	v_mov_b32_dpp v2, v1 row_bcast:31 row_mask:0xc bank_mask:0xf bound_ctrl:1
	v_add_f32_e32 v1, v1, v2
	s_nop 0
	v_readlane_b32 s1, v1, 63
	global_load_dword v1, v0, s[20:21] offset:512
	s_nop 0
	global_load_dword v0, v0, s[20:21] offset:768
	s_mov_b32 s20, 0x3fb8aa3b
	s_waitcnt vmcnt(0)
	v_mul_f32_e32 v2, v1, v0
	s_nop 1
	v_mov_b32_dpp v2, v2 quad_perm:[1,0,3,2] row_mask:0xf bank_mask:0xf bound_ctrl:1
	v_fmac_f32_e32 v2, v1, v0
	v_mov_b32_e32 v1, v3
	s_nop 0
	v_add_f32_dpp v0, v2, v2 quad_perm:[2,3,0,1] row_mask:0xf bank_mask:0xf bound_ctrl:1
	s_nop 1
	v_add_f32_dpp v0, v0, v0 row_ror:4 row_mask:0xf bank_mask:0xf bound_ctrl:1
	s_nop 1
	v_add_f32_dpp v0, v0, v0 row_ror:8 row_mask:0xf bank_mask:0xf bound_ctrl:1
	s_nop 1
	v_mov_b32_dpp v1, v0 row_bcast:15 row_mask:0xa bank_mask:0xf bound_ctrl:1
	v_add_f32_e32 v0, v0, v1
	v_mov_b32_e32 v1, v3
	s_nop 1
	v_mov_b32_dpp v1, v0 row_bcast:31 row_mask:0xc bank_mask:0xf bound_ctrl:1
	v_add_f32_e32 v0, v0, v1
	s_nop 0
	v_readlane_b32 s3, v0, 63
	v_cvt_f32_ubyte0_e32 v0, s2
	v_mul_f32_e32 v0, 0xbe99999a, v0
	v_mul_f32_e32 v1, 0x3fb8aa3b, v0
	v_fma_f32 v2, v0, s20, -v1
	v_rndne_f32_e32 v4, v1
	v_fmac_f32_e32 v2, 0x32a5705f, v0
	v_sub_f32_e32 v1, v1, v4
	v_add_f32_e32 v1, v1, v2
	v_exp_f32_e32 v1, v1
	v_cvt_i32_f32_e32 v2, v4
	s_mov_b32 s20, 0xc2ce8ed0
	v_cmp_ngt_f32_e32 vcc, s20, v0
	s_mov_b32 s20, 0x42b17218
	v_ldexp_f32 v1, v1, v2
	v_cndmask_b32_e32 v1, 0, v1, vcc
	v_cmp_nlt_f32_e32 vcc, s20, v0
	s_nop 1
	v_cndmask_b32_e32 v0, v190, v1, vcc
	v_mov_b32_e32 v1, 0x3f4ccccd
	v_fmamk_f32 v0, v0, 0xbf19999a, v1
	v_mul_f32_e32 v1, s1, v191
	v_fma_f32 v2, s1, v191, -v1
	v_rndne_f32_e32 v4, v1
	v_fmac_f32_e32 v2, s1, v252
	v_sub_f32_e32 v1, v1, v4
	v_add_f32_e32 v1, v1, v2
	v_exp_f32_e32 v1, v1
	v_cvt_i32_f32_e32 v2, v4
	v_cmp_nlt_f32_e32 vcc, s1, v199
	v_sub_f32_e32 v161, 1.0, v0
	v_ldexp_f32 v1, v1, v2
	v_mul_f32_e32 v2, s3, v191
	v_fma_f32 v4, s3, v191, -v2
	v_rndne_f32_e32 v5, v2
	v_fmac_f32_e32 v4, s3, v252
	v_sub_f32_e32 v2, v2, v5
	v_add_f32_e32 v2, v2, v4
	v_exp_f32_e32 v2, v2
	v_cvt_i32_f32_e32 v4, v5
	v_cndmask_b32_e32 v1, 0, v1, vcc
	v_cmp_ngt_f32_e32 vcc, s1, v194
	s_ashr_i32 s1, s0, 31
	v_ldexp_f32 v2, v2, v4
	v_cndmask_b32_e32 v1, v190, v1, vcc
	v_cmp_nlt_f32_e32 vcc, s3, v199
	s_lshl_b64 s[0:1], s[0:1], 2
	s_add_u32 s0, s96, s0
	v_cndmask_b32_e32 v2, 0, v2, vcc
	v_cmp_ngt_f32_e32 vcc, s3, v194
	s_addc_u32 s1, s97, s1
	s_lshl_b32 s2, s2, 9
	v_cndmask_b32_e32 v2, v190, v2, vcc
	v_sub_f32_e32 v1, v1, v2
	s_add_u32 s38, s18, s2
	v_add_f32_e32 v159, v0, v1
	s_addc_u32 s39, s19, 0
	v_readlane_b32 s0, v255, 16
	s_and_b32 s0, s0, 3
	s_lshl_b32 s0, s0, 9
	s_add_u32 s0, s0, 0x3600
	s_add_u32 s0, s98, s0
	s_addc_u32 s1, s99, 0
	s_branch .LBB0_85

.LBB0_85:
	v_cmp_eq_u32_e32 vcc, 0, v157
	s_barrier
	s_and_saveexec_b64 s[2:3], vcc
	s_cbranch_execz .LBB0_89
	s_getreg_b32 s40, hwreg(HW_REG_XCC_ID, 0, 4)
	s_and_b32 s40, s40, 7
	s_mov_b32 s41, 0
.Lq_try:
	s_add_u32 s20, s40, s41
	s_and_b32 s20, s20, 7
	s_lshl_b32 s21, s20, 6
	v_mov_b32_e32 v0, s21
	v_mov_b32_e32 v1, 1
	global_atomic_add v1, v0, v1, s[0:1] sc0
	s_waitcnt vmcnt(0)
	s_nop 0
	v_readfirstlane_b32 s24, v1
	s_nop 3
	s_cmpk_lt_u32 s24, 0x80
	s_cbranch_scc1 .Lq_got
	s_add_u32 s41, s41, 1
	s_cmp_lt_u32 s41, 8
	s_cbranch_scc1 .Lq_try
	s_movk_i32 s24, 0x400
	s_branch .Lq_store
.Lq_got:
	s_lshr_b32 s21, s24, 2
	s_lshl_b32 s21, s21, 5
	s_and_b32 s24, s24, 3
	s_lshl_b32 s20, s20, 2
	s_or_b32 s24, s24, s20
	s_or_b32 s24, s24, s21
.Lq_store:
	v_mov_b32_e32 v0, s24
	ds_write_b32 v183, v0
.LBB0_89:
	s_or_b64 exec, exec, s[2:3]
	s_waitcnt lgkmcnt(0)
	s_barrier
	ds_read_b32 v0, v183
	s_movk_i32 s2, 0x3ff
	s_waitcnt lgkmcnt(0)
	v_cmp_lt_u32_e32 vcc, s2, v0
	v_readfirstlane_b32 s41, v0
	s_mov_b64 s[2:3], -1
	s_cbranch_vccnz .LBB0_84
	s_movk_i32 s2, 0x7f
	s_and_b32 s40, s41, 3
	s_mov_b32 s58, s41
	v_cmp_lt_i32_e32 vcc, s2, v157
	v_mov_b32_e32 v0, 0xf149f2ca
	s_barrier
	s_and_saveexec_b64 s[2:3], vcc
	s_cbranch_execz .LBB0_94
	s_movk_i32 s20, 0x8f
	v_add_u32_e32 v0, 0xffffff80, v157
	v_cmp_lt_u32_e32 vcc, s20, v157
	s_and_saveexec_b64 s[20:21], vcc
	s_cbranch_execz .LBB0_93
	v_cvt_f32_u32_e32 v0, v0
	s_mov_b32 s24, 0x40051592
	v_mul_f32_e32 v0, 0x3d800000, v0
	v_cmp_gt_f32_e32 vcc, s50, v0
	s_nop 1
	v_cndmask_b32_e64 v1, 0, 32, vcc
	v_ldexp_f32 v0, v0, v1
	v_log_f32_e32 v0, v0
	v_cndmask_b32_e32 v1, 0, v195, vcc
	v_mul_f32_e32 v2, 0x3f317217, v0
	v_fma_f32 v2, v0, s54, -v2
	v_fmac_f32_e32 v2, 0x3377d1cf, v0
	v_fmac_f32_e32 v2, 0x3f317217, v0
	v_cmp_lt_f32_e64 vcc, |v0|, s53
	s_nop 1
	v_cndmask_b32_e32 v0, v0, v2, vcc
	v_sub_f32_e32 v0, v0, v1
	v_div_scale_f32 v1, s[42:43], s24, s24, v0
	v_rcp_f32_e32 v2, v1
	v_div_scale_f32 v4, vcc, v0, s24, v0
	v_fma_f32 v5, -v1, v2, 1.0
	v_fmac_f32_e32 v2, v5, v2
	v_mul_f32_e32 v5, v4, v2
	v_fma_f32 v6, -v1, v5, v4
	v_fmac_f32_e32 v5, v6, v2
	v_fma_f32 v1, -v1, v5, v4
	v_div_fmas_f32 v1, v1, v2, v5
	v_div_fixup_f32 v0, v1, s24, v0
	v_mul_f32_e32 v0, 0x41800000, v0
	v_cvt_i32_f32_e32 v0, v0
	v_min_i32_e32 v0, 15, v0
	v_add_u32_e32 v0, 16, v0

.LBB0_94:
	s_or_b64 exec, exec, s[2:3]
	s_lshr_b32 s20, s41, 5
	v_ashrrev_i32_e32 v2, 6, v157
	s_lshl_b32 s2, s20, 7
	s_xor_b32 s42, s2, 0xf80
	v_lshlrev_b32_e32 v8, 5, v2
	v_and_b32_e32 v6, 31, v157
	v_add_u32_e32 v1, s42, v8
	s_lshl_b32 s2, s41, 10
	v_or_b32_e32 v4, v1, v6
	s_and_b32 s24, s2, 0x7000
	v_lshlrev_b32_e32 v1, 2, v157
	s_lshl_b32 s2, s40, 2
	v_readlane_b32 s60, v253, 7
	ds_write_b32 v1, v0 offset:49152
	v_mov_b32_e32 v0, s2
	v_readlane_b32 s70, v253, 17
	v_readlane_b32 s71, v253, 18
	s_lshl_b32 s2, s41, 7
	v_ashrrev_i32_e32 v5, 31, v4
	v_bfe_u32 v1, v157, 4, 2
	s_and_b32 s2, s2, 0xf80
	v_lshl_add_u64 v[144:145], v[4:5], 0, s[24:25]
	global_load_dword v9, v0, s[70:71] offset:496
	v_and_b32_e32 v0, 7, v157
	v_bfe_u32 v4, v157, 3, 3
	v_bitop3_b32 v11, v1, v0, 4 bitop3:0x36
	v_add_u32_e32 v0, s2, v8
	v_readlane_b32 s61, v253, 8
	v_readlane_b32 s62, v253, 9
	v_readlane_b32 s63, v253, 10
	v_readlane_b32 s64, v253, 11
	v_readlane_b32 s65, v253, 12
	v_readlane_b32 s66, v253, 13
	v_readlane_b32 s67, v253, 14
	v_readlane_b32 s68, v253, 15
	v_readlane_b32 s69, v253, 16
	v_readlane_b32 s72, v253, 19
	v_readlane_b32 s73, v253, 20
	v_readlane_b32 s74, v253, 21
	v_readlane_b32 s75, v253, 22
	v_or_b32_e32 v0, v0, v4
	v_bitop3_b32 v10, v1, v157, 7 bitop3:0x78
	v_ashrrev_i32_e32 v1, 31, v0
	v_readlane_b32 s60, v254, 44
	v_lshlrev_b64 v[0:1], 13, v[0:1]
	v_readlane_b32 s61, v254, 45
	v_readlane_b32 s4, v254, 62
	v_readlane_b32 s18, v255, 12
	v_lshl_add_u64 v[150:151], s[60:61], 0, v[0:1]
	v_lshl_add_u32 v0, v2, 4, s24
	v_readlane_b32 s19, v255, 13
	v_or_b32_e32 v4, v0, v4
	v_bfe_u32 v7, v157, 5, 1
	v_mov_b64_e32 v[0:1], s[18:19]
	v_mad_i64_i32 v[4:5], s[2:3], v4, s51, v[0:1]
	v_mad_u64_u32 v[0:1], s[2:3], v144, s51, v[0:1]
	v_mad_i32_i24 v1, v145, s51, v1
	s_lshl_b32 s24, s40, 8
	v_lshlrev_b32_e32 v147, 11, v2
	v_lshlrev_b32_e32 v202, 12, v2
	v_lshl_add_u64 v[148:149], v[0:1], 0, s[24:25]
	v_lshlrev_b32_e32 v2, 4, v7
	v_lshl_add_u64 v[164:165], v[148:149], 0, v[2:3]
	v_lshl_add_u64 v[162:163], v[4:5], 0, s[24:25]
	v_lshlrev_b32_e32 v2, 4, v10
	v_lshl_add_u64 v[152:153], v[162:163], 0, v[2:3]
	v_readfirstlane_b32 s2, v147
	v_lshl_add_u64 v[0:1], v[152:153], 0, s[28:29]
	s_mov_b32 m0, s2
	global_load_dwordx4 v[128:131], v[164:165], off
	global_load_dwordx4 v[132:135], v[164:165], off offset:32
	global_load_dwordx4 v[136:139], v[164:165], off offset:64
	global_load_dwordx4 v[140:143], v[164:165], off offset:96
	s_waitcnt lgkmcnt(0)
	s_barrier
	global_load_lds_dwordx4 v[0:1], off
	v_lshlrev_b32_e32 v0, 4, v11
	v_mov_b32_e32 v1, v3
	v_or_b32_e32 v12, 0x400, v147
	v_lshl_add_u64 v[154:155], v[162:163], 0, v[0:1]
	s_mov_b64 s[2:3], 0xec00
	v_add_u32_e32 v210, 0x4000, v202
	v_lshl_add_u64 v[4:5], v[154:155], 0, s[2:3]
	v_readfirstlane_b32 s2, v12
	s_mov_b32 m0, s2
	v_readfirstlane_b32 s2, v210
	global_load_lds_dwordx4 v[4:5], off
	s_mov_b32 m0, s2
	v_lshl_add_u64 v[0:1], v[150:151], 0, v[0:1]
	s_mov_b64 s[2:3], 0x10000
	v_add_u32_e32 v211, 0x4400, v202
	v_lshl_add_u64 v[166:167], v[150:151], 0, v[2:3]
	v_lshl_add_u64 v[168:169], v[0:1], 0, s[2:3]
	v_readfirstlane_b32 s2, v211
	global_load_lds_dwordx4 v[166:167], off
	s_mov_b32 m0, s2
	s_mov_b64 s[2:3], 0x20000
	v_add_u32_e32 v212, 0x4800, v202
	v_lshl_add_u64 v[170:171], v[166:167], 0, s[2:3]
	v_readfirstlane_b32 s2, v212
	global_load_lds_dwordx4 v[168:169], off
	s_mov_b32 m0, s2
	s_mov_b64 s[2:3], 0x30000
	v_add_u32_e32 v213, 0x4c00, v202
	v_lshl_add_u64 v[172:173], v[0:1], 0, s[2:3]
	v_readfirstlane_b32 s2, v213
	global_load_lds_dwordx4 v[170:171], off
	s_mov_b32 m0, s2
	v_lshrrev_b32_e32 v0, 1, v157
	global_load_lds_dwordx4 v[172:173], off
	v_bfe_u32 v1, v157, 1, 3
	v_bitop3_b32 v0, v7, v0, 7 bitop3:0x78
	v_lshlrev_b32_e32 v205, 4, v0
	v_bitop3_b32 v0, v7, v1, 2 bitop3:0x36
	s_lshl_b32 s2, s20, 1
	v_lshlrev_b32_e32 v206, 4, v0
	v_bitop3_b32 v0, v7, v1, 4 bitop3:0x36
	s_sub_i32 s20, 64, s2
	v_lshlrev_b32_e32 v207, 4, v0
	v_bitop3_b32 v0, v7, v1, 6 bitop3:0x36
	s_sub_i32 s2, s42, 59
	v_lshlrev_b32_e32 v146, 2, v7
	s_waitcnt vmcnt(0)
	v_lshlrev_b32_e32 v208, 4, v0
	v_add3_u32 v0, s2, v8, v6
	v_mov_b32_e32 v14, v3
	v_mov_b32_e32 v15, v3
	s_waitcnt vmcnt(0)
	v_mul_f32_e32 v203, 0x3fb8aa3b, v9
	v_lshlrev_b32_e32 v176, 3, v10
	v_lshlrev_b32_e32 v174, 3, v11
	v_lshlrev_b32_e32 v204, 7, v6
	v_sub_u32_e32 v209, v0, v146
	s_mov_b32 s24, 0
	v_mov_b32_e32 v0, v3
	v_mov_b32_e32 v1, v3
	v_mov_b32_e32 v2, v3
	v_mov_b32_e32 v4, v3
	v_mov_b32_e32 v5, v3
	v_mov_b32_e32 v6, v3
	v_mov_b32_e32 v7, v3
	v_mov_b32_e32 v8, v3
	v_mov_b32_e32 v9, v3
	v_mov_b32_e32 v10, v3
	v_mov_b32_e32 v11, v3
	v_mov_b32_e32 v12, v3
	v_mov_b32_e32 v13, v3
	v_mov_b64_e32 v[30:31], v[14:15]
	v_mov_b64_e32 v[46:47], v[14:15]
	v_mov_b64_e32 v[62:63], v[14:15]
	v_mov_b64_e32 v[78:79], v[14:15]
	s_lshl_b32 s21, s40, 7
	v_mov_b32_e32 v216, 0xf149f2ca
	v_mov_b32_e32 v215, 0
	v_mov_b32_e32 v214, v209
	v_mov_b64_e32 v[28:29], v[12:13]
	v_mov_b64_e32 v[26:27], v[10:11]
	v_mov_b64_e32 v[24:25], v[8:9]
	v_mov_b64_e32 v[22:23], v[6:7]
	v_mov_b64_e32 v[20:21], v[4:5]
	v_mov_b64_e32 v[18:19], v[2:3]
	v_mov_b64_e32 v[16:17], v[0:1]
	v_mov_b64_e32 v[44:45], v[12:13]
	v_mov_b64_e32 v[42:43], v[10:11]
	v_mov_b64_e32 v[40:41], v[8:9]
	v_mov_b64_e32 v[38:39], v[6:7]
	v_mov_b64_e32 v[36:37], v[4:5]
	v_mov_b64_e32 v[34:35], v[2:3]
	v_mov_b64_e32 v[32:33], v[0:1]
	v_mov_b64_e32 v[60:61], v[12:13]
	v_mov_b64_e32 v[58:59], v[10:11]
	v_mov_b64_e32 v[56:57], v[8:9]
	v_mov_b64_e32 v[54:55], v[6:7]
	v_mov_b64_e32 v[52:53], v[4:5]
	v_mov_b64_e32 v[50:51], v[2:3]
	v_mov_b64_e32 v[48:49], v[0:1]
	v_mov_b64_e32 v[76:77], v[12:13]
	v_mov_b64_e32 v[74:75], v[10:11]
	v_mov_b64_e32 v[72:73], v[8:9]
	v_mov_b64_e32 v[70:71], v[6:7]
	v_mov_b64_e32 v[68:69], v[4:5]
	v_mov_b64_e32 v[66:67], v[2:3]
	v_mov_b64_e32 v[64:65], v[0:1]
	s_mov_b32 s2, s24
	v_readlane_b32 s62, v254, 46
	v_readlane_b32 s63, v254, 47
	v_readlane_b32 s64, v254, 48
	v_readlane_b32 s65, v254, 49
	v_readlane_b32 s66, v254, 50
	v_readlane_b32 s67, v254, 51
	v_readlane_b32 s68, v254, 52
	v_readlane_b32 s69, v254, 53
	v_readlane_b32 s70, v254, 54
	v_readlane_b32 s71, v254, 55
	v_readlane_b32 s72, v254, 56
	v_readlane_b32 s73, v254, 57
	v_readlane_b32 s74, v254, 58
	v_readlane_b32 s75, v254, 59
	v_readlane_b32 s5, v254, 63
	v_readlane_b32 s6, v255, 0
	v_readlane_b32 s7, v255, 1
	v_readlane_b32 s8, v255, 2
	v_readlane_b32 s9, v255, 3
	v_readlane_b32 s10, v255, 4
	v_readlane_b32 s11, v255, 5
	v_readlane_b32 s12, v255, 6
	v_readlane_b32 s13, v255, 7
	v_readlane_b32 s14, v255, 8
	v_readlane_b32 s15, v255, 9
	v_readlane_b32 s16, v255, 10
	v_readlane_b32 s17, v255, 11
	s_waitcnt lgkmcnt(0)
	s_barrier
	s_lshr_b32 s59, s58, 2
	s_and_b32 s59, s59, 7
	s_and_b32 s3, s58, 3
	s_lshl_b32 s46, s59, 2
	s_add_u32 s46, s46, s3
	s_lshl_b32 s46, s46, 20
	v_readlane_b32 s48, v254, 44
	v_readlane_b32 s49, v254, 45
	s_nop 0
	s_add_u32 s46, s48, s46
	s_addc_u32 s47, s49, 0
	s_add_u32 s46, s46, 0x80
	s_addc_u32 s47, s47, 0
	s_add_u32 s48, s46, 0x20000
	s_addc_u32 s49, s47, 0
	s_mul_i32 s44, s59, 0x1d00000
	s_lshl_b32 s3, s3, 8
	s_add_u32 s44, s44, s3
	s_add_u32 s44, s44, 0x74400
	v_readlane_b32 s3, v255, 12
	v_readlane_b32 s59, v255, 13
	s_nop 0
	s_add_u32 s44, s3, s44
	s_addc_u32 s45, s59, 0
	s_add_i32 s40, s2, 1
	s_cmp_ge_u32 s40, s20
	v_lshlrev_b32_e32 v2, 1, v176
	s_cbranch_scc1 .LBB0_96
.LBB0_95:
	s_and_b32 s3, s40, 1
	s_lshl_b32 s59, s3, 13
	s_add_u32 s59, s59, s76
	s_mov_b32 m0, s59
	s_add_u32 s59, s59, 0x400
	global_load_lds_dwordx4 v226, s[44:45]
	s_mov_b32 m0, s59
	s_lshl_b32 s59, s3, 14
	global_load_lds_dwordx4 v227, s[44:45]
	s_add_u32 s59, s59, s77
	s_mov_b32 m0, s59
	s_add_u32 s59, s59, 0x400
	global_load_lds_dwordx4 v228, s[46:47]
	s_mov_b32 m0, s59
	s_add_u32 s59, s59, 0x400
	global_load_lds_dwordx4 v229, s[46:47]
	s_mov_b32 m0, s59
	s_add_u32 s59, s59, 0x400
	global_load_lds_dwordx4 v228, s[48:49]
	s_mov_b32 m0, s59
	s_add_u32 s44, s44, 0x74000
	global_load_lds_dwordx4 v229, s[48:49]
	s_addc_u32 s45, s45, 0
	s_add_u32 s46, s46, 0x80
	s_addc_u32 s47, s47, 0
	s_add_u32 s48, s48, 0x80
	s_addc_u32 s49, s49, 0

.LBB0_104:
	v_and_b32_e32 v1, 64, v198
	v_xor_b32_e32 v0, 32, v198
	v_add_u32_e32 v1, 64, v1
	v_cmp_lt_i32_e32 vcc, v0, v1
	v_readlane_b32 s60, v254, 44
	v_readlane_b32 s62, v254, 46
	v_cndmask_b32_e32 v0, v198, v0, vcc
	v_lshlrev_b32_e32 v176, 2, v0
	ds_bpermute_b32 v0, v176, v81
	v_readlane_b32 s63, v254, 47
	s_lshl_b32 s24, s21, 1
	v_mov_b32_e32 v10, v3
	v_mov_b32_e32 v11, v3
	s_waitcnt lgkmcnt(0)
	v_add_f32_e32 v4, v81, v0
	v_div_scale_f32 v5, s[2:3], v4, v4, 1.0
	v_rcp_f32_e32 v6, v5
	v_div_scale_f32 v7, vcc, 1.0, v4, 1.0
	v_lshlrev_b64 v[0:1], 11, v[144:145]
	v_fma_f32 v8, -v5, v6, 1.0
	v_fmac_f32_e32 v6, v8, v6
	v_mul_f32_e32 v8, v7, v6
	v_fma_f32 v9, -v5, v8, v7
	v_fmac_f32_e32 v8, v9, v6
	v_fma_f32 v5, -v5, v8, v7
	v_div_fmas_f32 v5, v5, v6, v8
	v_lshl_add_u64 v[0:1], s[62:63], 0, v[0:1]
	v_div_fixup_f32 v4, v5, v4, 1.0
	v_lshl_add_u64 v[0:1], v[0:1], 0, s[24:25]
	v_lshlrev_b32_e32 v6, 1, v146
	v_mov_b32_e32 v7, v3
	v_lshl_add_u64 v[144:145], v[0:1], 0, v[6:7]
	v_pk_mul_f32 v[0:1], v[64:65], v[4:5] op_sel_hi:[1,0]
	v_pk_mul_f32 v[6:7], v[66:67], v[4:5] op_sel_hi:[1,0]
	v_cvt_pk_bf16_f32 v0, v0, v1
	v_cvt_pk_bf16_f32 v1, v6, v7
	global_store_dwordx2 v[144:145], v[0:1], off
	v_pk_mul_f32 v[0:1], v[68:69], v[4:5] op_sel_hi:[1,0]
	v_pk_mul_f32 v[6:7], v[70:71], v[4:5] op_sel_hi:[1,0]
	v_cvt_pk_bf16_f32 v0, v0, v1
	v_cvt_pk_bf16_f32 v1, v6, v7
	global_store_dwordx2 v[144:145], v[0:1], off offset:16
	v_pk_mul_f32 v[0:1], v[72:73], v[4:5] op_sel_hi:[1,0]
	v_pk_mul_f32 v[6:7], v[74:75], v[4:5] op_sel_hi:[1,0]
	v_cvt_pk_bf16_f32 v0, v0, v1
	v_cvt_pk_bf16_f32 v1, v6, v7
	global_store_dwordx2 v[144:145], v[0:1], off offset:32
	v_pk_mul_f32 v[0:1], v[76:77], v[4:5] op_sel_hi:[1,0]
	v_pk_mul_f32 v[6:7], v[78:79], v[4:5] op_sel_hi:[1,0]
	v_cvt_pk_bf16_f32 v0, v0, v1
	v_cvt_pk_bf16_f32 v1, v6, v7
	global_store_dwordx2 v[144:145], v[0:1], off offset:48
	v_pk_mul_f32 v[0:1], v[48:49], v[4:5] op_sel_hi:[1,0]
	v_pk_mul_f32 v[6:7], v[50:51], v[4:5] op_sel_hi:[1,0]
	v_cvt_pk_bf16_f32 v0, v0, v1
	v_cvt_pk_bf16_f32 v1, v6, v7
	global_store_dwordx2 v[144:145], v[0:1], off offset:64
	v_pk_mul_f32 v[0:1], v[52:53], v[4:5] op_sel_hi:[1,0]
	v_pk_mul_f32 v[6:7], v[54:55], v[4:5] op_sel_hi:[1,0]
	v_cvt_pk_bf16_f32 v0, v0, v1
	v_cvt_pk_bf16_f32 v1, v6, v7
	global_store_dwordx2 v[144:145], v[0:1], off offset:80
	v_pk_mul_f32 v[0:1], v[56:57], v[4:5] op_sel_hi:[1,0]
	v_pk_mul_f32 v[6:7], v[58:59], v[4:5] op_sel_hi:[1,0]
	v_cvt_pk_bf16_f32 v0, v0, v1
	v_cvt_pk_bf16_f32 v1, v6, v7
	global_store_dwordx2 v[144:145], v[0:1], off offset:96
	v_pk_mul_f32 v[0:1], v[60:61], v[4:5] op_sel_hi:[1,0]
	v_pk_mul_f32 v[6:7], v[62:63], v[4:5] op_sel_hi:[1,0]
	v_cvt_pk_bf16_f32 v0, v0, v1
	v_cvt_pk_bf16_f32 v1, v6, v7
	global_store_dwordx2 v[144:145], v[0:1], off offset:112
	v_pk_mul_f32 v[0:1], v[32:33], v[4:5] op_sel_hi:[1,0]
	v_pk_mul_f32 v[6:7], v[34:35], v[4:5] op_sel_hi:[1,0]
	v_cvt_pk_bf16_f32 v0, v0, v1
	v_cvt_pk_bf16_f32 v1, v6, v7
	global_store_dwordx2 v[144:145], v[0:1], off offset:128
	v_pk_mul_f32 v[0:1], v[36:37], v[4:5] op_sel_hi:[1,0]
	v_pk_mul_f32 v[6:7], v[38:39], v[4:5] op_sel_hi:[1,0]
	v_cvt_pk_bf16_f32 v0, v0, v1
	v_cvt_pk_bf16_f32 v1, v6, v7
	global_store_dwordx2 v[144:145], v[0:1], off offset:144
	v_pk_mul_f32 v[0:1], v[40:41], v[4:5] op_sel_hi:[1,0]
	v_pk_mul_f32 v[6:7], v[42:43], v[4:5] op_sel_hi:[1,0]
	v_cvt_pk_bf16_f32 v0, v0, v1
	v_cvt_pk_bf16_f32 v1, v6, v7
	global_store_dwordx2 v[144:145], v[0:1], off offset:160
	v_pk_mul_f32 v[0:1], v[44:45], v[4:5] op_sel_hi:[1,0]
	v_pk_mul_f32 v[6:7], v[46:47], v[4:5] op_sel_hi:[1,0]
	v_cvt_pk_bf16_f32 v0, v0, v1
	v_cvt_pk_bf16_f32 v1, v6, v7
	global_store_dwordx2 v[144:145], v[0:1], off offset:176
	v_pk_mul_f32 v[0:1], v[16:17], v[4:5] op_sel_hi:[1,0]
	v_pk_mul_f32 v[6:7], v[18:19], v[4:5] op_sel_hi:[1,0]
	v_cvt_pk_bf16_f32 v0, v0, v1
	v_cvt_pk_bf16_f32 v1, v6, v7
	global_store_dwordx2 v[144:145], v[0:1], off offset:192
	v_pk_mul_f32 v[0:1], v[20:21], v[4:5] op_sel_hi:[1,0]
	v_pk_mul_f32 v[6:7], v[22:23], v[4:5] op_sel_hi:[1,0]
	v_cvt_pk_bf16_f32 v0, v0, v1
	v_cvt_pk_bf16_f32 v1, v6, v7
	global_store_dwordx2 v[144:145], v[0:1], off offset:208
	v_pk_mul_f32 v[0:1], v[24:25], v[4:5] op_sel_hi:[1,0]
	v_pk_mul_f32 v[6:7], v[26:27], v[4:5] op_sel_hi:[1,0]
	v_cvt_pk_bf16_f32 v0, v0, v1
	v_cvt_pk_bf16_f32 v1, v6, v7
	global_store_dwordx2 v[144:145], v[0:1], off offset:224
	v_pk_mul_f32 v[0:1], v[28:29], v[4:5] op_sel_hi:[1,0]
	v_pk_mul_f32 v[4:5], v[30:31], v[4:5] op_sel_hi:[1,0]
	v_cvt_pk_bf16_f32 v0, v0, v1
	v_cvt_pk_bf16_f32 v1, v4, v5
	s_mov_b64 s[2:3], 0x480
	global_store_dwordx2 v[144:145], v[0:1], off offset:240
	v_lshl_add_u64 v[0:1], v[152:153], 0, s[2:3]
	v_readfirstlane_b32 s2, v147
	global_load_dwordx4 v[128:131], v[164:165], off offset:128
	global_load_dwordx4 v[132:135], v[164:165], off offset:160
	global_load_dwordx4 v[136:139], v[164:165], off offset:192
	global_load_dwordx4 v[140:143], v[164:165], off offset:224
	s_mov_b32 m0, s2
	v_lshlrev_b32_e32 v164, 1, v174
	v_mov_b32_e32 v165, v3
	s_barrier
	global_load_lds_dwordx4 v[0:1], off
	v_lshl_add_u64 v[0:1], v[162:163], 0, v[164:165]
	s_mov_b64 s[2:3], 0xec80
	v_add_u32_e32 v4, 0x400, v147
	v_lshl_add_u64 v[0:1], v[0:1], 0, s[2:3]
	v_readfirstlane_b32 s2, v4
	s_mov_b32 m0, s2
	v_readfirstlane_b32 s2, v210
	global_load_lds_dwordx4 v[0:1], off
	s_mov_b32 m0, s2
	v_readfirstlane_b32 s2, v211
	global_load_lds_dwordx4 v[166:167], off
	s_mov_b32 m0, s2
	v_readfirstlane_b32 s2, v212
	global_load_lds_dwordx4 v[168:169], off
	s_mov_b32 m0, s2
	v_readfirstlane_b32 s2, v213
	global_load_lds_dwordx4 v[170:171], off
	s_mov_b32 m0, s2
	v_mov_b32_e32 v18, v3
	global_load_lds_dwordx4 v[172:173], off
	s_waitcnt vmcnt(0)
	v_mov_b32_e32 v19, v3
	s_mov_b32 s2, 0
	v_mov_b32_e32 v4, v3
	v_mov_b32_e32 v5, v3
	v_mov_b32_e32 v6, v3
	v_mov_b32_e32 v7, v3
	v_mov_b32_e32 v8, v3
	v_mov_b32_e32 v9, v3
	v_mov_b32_e32 v12, v3
	v_mov_b32_e32 v13, v3
	v_mov_b32_e32 v14, v3
	v_mov_b32_e32 v15, v3
	v_mov_b32_e32 v16, v3
	v_mov_b32_e32 v17, v3
	v_mov_b64_e32 v[34:35], v[18:19]
	v_mov_b64_e32 v[50:51], v[18:19]
	v_mov_b64_e32 v[66:67], v[18:19]
	v_mov_b32_e32 v169, 0xf149f2ca
	v_mov_b32_e32 v168, 0
	s_mov_b32 s24, s2
	v_mov_b64_e32 v[32:33], v[16:17]
	v_mov_b64_e32 v[30:31], v[14:15]
	v_mov_b64_e32 v[28:29], v[12:13]
	v_mov_b64_e32 v[26:27], v[10:11]
	v_mov_b64_e32 v[24:25], v[8:9]
	v_mov_b64_e32 v[22:23], v[6:7]
	v_mov_b64_e32 v[20:21], v[4:5]
	v_mov_b64_e32 v[48:49], v[16:17]
	v_mov_b64_e32 v[46:47], v[14:15]
	v_mov_b64_e32 v[44:45], v[12:13]
	v_mov_b64_e32 v[42:43], v[10:11]
	v_mov_b64_e32 v[40:41], v[8:9]
	v_mov_b64_e32 v[38:39], v[6:7]
	v_mov_b64_e32 v[36:37], v[4:5]
	v_mov_b64_e32 v[64:65], v[16:17]
	v_mov_b64_e32 v[62:63], v[14:15]
	v_mov_b64_e32 v[60:61], v[12:13]
	v_mov_b64_e32 v[58:59], v[10:11]
	v_mov_b64_e32 v[56:57], v[8:9]
	v_mov_b64_e32 v[54:55], v[6:7]
	v_mov_b64_e32 v[52:53], v[4:5]
	v_readlane_b32 s61, v254, 45
	v_readlane_b32 s64, v254, 48
	v_readlane_b32 s65, v254, 49
	v_readlane_b32 s66, v254, 50
	v_readlane_b32 s67, v254, 51
	v_readlane_b32 s68, v254, 52
	v_readlane_b32 s69, v254, 53
	v_readlane_b32 s70, v254, 54
	v_readlane_b32 s71, v254, 55
	v_readlane_b32 s72, v254, 56
	v_readlane_b32 s73, v254, 57
	v_readlane_b32 s74, v254, 58
	v_readlane_b32 s75, v254, 59
	s_waitcnt vmcnt(0) lgkmcnt(0)
	s_barrier
	s_lshr_b32 s59, s58, 2
	s_and_b32 s59, s59, 7
	s_and_b32 s3, s58, 3
	s_lshl_b32 s46, s59, 2
	s_add_u32 s46, s46, s3
	s_lshl_b32 s46, s46, 20
	v_readlane_b32 s48, v254, 44
	v_readlane_b32 s49, v254, 45
	s_nop 0
	s_add_u32 s46, s48, s46
	s_addc_u32 s47, s49, 0
	s_add_u32 s46, s46, 0x80
	s_addc_u32 s47, s47, 0
	s_add_u32 s48, s46, 0x20000
	s_addc_u32 s49, s47, 0
	s_mul_i32 s44, s59, 0x1d00000
	s_lshl_b32 s3, s3, 8
	s_add_u32 s44, s44, s3
	s_add_u32 s44, s44, 0x74480
	v_readlane_b32 s3, v255, 12
	v_readlane_b32 s59, v255, 13
	s_nop 0
	s_add_u32 s44, s3, s44
	s_addc_u32 s45, s59, 0
	s_add_i32 s21, s2, 1
	s_cmp_ge_u32 s21, s20
	s_cbranch_scc1 .LBB0_106
.LBB0_105:
	s_and_b32 s3, s21, 1
	s_lshl_b32 s59, s3, 13
	s_add_u32 s59, s59, s76
	s_mov_b32 m0, s59
	s_add_u32 s59, s59, 0x400
	global_load_lds_dwordx4 v226, s[44:45]
	s_mov_b32 m0, s59
	s_lshl_b32 s59, s3, 14
	global_load_lds_dwordx4 v227, s[44:45]
	s_add_u32 s59, s59, s77
	s_mov_b32 m0, s59
	s_add_u32 s59, s59, 0x400
	global_load_lds_dwordx4 v228, s[46:47]
	s_mov_b32 m0, s59
	s_add_u32 s59, s59, 0x400
	global_load_lds_dwordx4 v229, s[46:47]
	s_mov_b32 m0, s59
	s_add_u32 s59, s59, 0x400
	global_load_lds_dwordx4 v228, s[48:49]
	s_mov_b32 m0, s59
	s_add_u32 s44, s44, 0x74000
	global_load_lds_dwordx4 v229, s[48:49]
	s_addc_u32 s45, s45, 0
	s_add_u32 s46, s46, 0x80
	s_addc_u32 s47, s47, 0
	s_add_u32 s48, s48, 0x80
	s_addc_u32 s49, s49, 0
